# baseline (speedup 1.0000x reference)
; template <int DQK, int MODE> ...
;     ...
;   struct TRegs { u32x4 k[NKL]; u32x4 v[2]; };
;   auto gload = [&](TRegs& R, int j) {
; #pragma unroll
;     for (int i = 0; i < NKL; ++i) {
;       int c = tid + i * 256;
;       int row = c / KCH, cc = c % KCH;
;       R.k[i] = *(const u32x4*)(Kp + (long)(j * 64 + row) * kld + cc * 8);
;     }
; #pragma unroll
;     for (int i = 0; i < 2; ++i) {
;       int c = tid + i * 256;
;       int d = c >> 3, cc = c & 7;
;       R.v[i] = *(const u32x4*)(VTp + (long)j * 4096 + d * 64 + cc * 8);
;     }
;   };
;   auto lstore = [&](const TRegs& R, int st) {
;     u16* Ks = lds + st * STG;
;     u16* Vs = Ks + KT;
; #pragma unroll
;     for (int i = 0; i < NKL; ++i) {
;       int c = tid + i * 256;
;       int row = c / KCH, cc = c % KCH;
;       *(u32x4*)(Ks + row * KST + cc * 8) = R.k[i];
;     }
; #pragma unroll
;     for (int i = 0; i < 2; ++i) {
;       int c = tid + i * 256;
;       int d = c >> 3, cc = c & 7;
;       u32x2 lo = {R.v[i].x, R.v[i].y}, hi = {R.v[i].z, R.v[i].w};
;       *(u32x2*)(Vs + d * VST + cc * 8) = lo;
;       *(u32x2*)(Vs + d * VST + cc * 8 + 4) = hi;
;     }
;   };
;   f32x16 O[2];
; #pragma unroll
;   for (int du = 0; du < 2; ++du)
; #pragma unroll
;     for (int r = 0; r < 16; ++r) O[du][r] = 0.f;
;   float m_run = 0.f, lsum = 0.f;
;   bool first = true;
;   float carry = active ? 1.f : 0.f;
;   const int dir = (MODE == 2) ? -1 : 1;
;   const int jstart = (MODE == 2) ? jhi : jlo;
;   const int ntile = jhi - jlo + 1;
;     ...
;   {
;     TRegs R0, R1;
;     gload(R0, jstart);
;     if (ntile > 1) gload(R1, jstart + dir);
.LBB0_874:
	s_or_b64 exec, exec, s[10:11]
	v_ashrrev_i32_e32 v4, 31, v6
	v_lshrrev_b32_e32 v4, 29, v4
	s_add_i32 s5, s7, 2
	v_add_u32_e32 v5, v6, v4
	s_and_b64 s[10:11], exec, s[0:1]
	s_load_dwordx8 s[12:19], s[28:29], 0x180
	v_ashrrev_i32_e32 v4, 3, v5
	v_and_b32_e32 v5, -8, v5
	v_readlane_b32 s10, v252, 20
	v_sub_u32_e32 v32, v6, v5
	v_ashrrev_i32_e32 v5, 31, v4
	s_cselect_b32 s10, s10, s5
	v_lshlrev_b64 v[8:9], 9, v[4:5]
	v_add_u32_e32 v5, 0x100, v6
	s_ashr_i32 s11, s10, 31
	v_ashrrev_i32_e32 v14, 31, v5
	s_lshl_b64 s[10:11], s[10:11], 17
	v_lshrrev_b32_e32 v14, 29, v14
	s_waitcnt lgkmcnt(0)
	s_add_u32 s5, s12, s10
	v_add_u32_e32 v15, v5, v14
	s_addc_u32 s13, s13, s11
	v_ashrrev_i32_e32 v14, 3, v15
	v_and_b32_e32 v15, -8, v15
	s_add_u32 s12, s5, s3
	v_sub_u32_e32 v33, v5, v15
	v_ashrrev_i32_e32 v15, 31, v14
	s_addc_u32 s13, s13, 0
	v_lshlrev_b32_e32 v12, 3, v32
	v_lshlrev_b64 v[16:17], 9, v[14:15]
	v_lshlrev_b32_e32 v15, 3, v6
	s_add_u32 s3, s14, s10
	v_ashrrev_i32_e32 v13, 31, v12
	v_lshlrev_b32_e32 v20, 3, v33
	v_and_b32_e32 v22, 0xffffffc0, v15
	s_addc_u32 s5, s15, s11
	s_lshl_b32 s10, s2, 15
	v_lshl_add_u64 v[10:11], s[12:13], 0, v[8:9]
	v_lshlrev_b64 v[12:13], 1, v[12:13]
	v_ashrrev_i32_e32 v21, 31, v20
	v_ashrrev_i32_e32 v23, 31, v22
	s_add_u32 s10, s3, s10
	v_lshl_add_u64 v[10:11], v[10:11], 0, v[12:13]
	v_lshl_add_u64 v[18:19], s[12:13], 0, v[16:17]
	v_lshlrev_b64 v[20:21], 1, v[20:21]
	v_lshlrev_b64 v[24:25], 1, v[22:23]
	v_add_u32_e32 v22, 0x800, v22
	s_mov_b32 s3, 0x8000
	s_addc_u32 s11, s5, 0
	v_lshl_add_u64 v[18:19], v[18:19], 0, v[20:21]
	global_load_dwordx4 v[84:87], v[10:11], off
	global_load_dwordx4 v[88:91], v[18:19], off
	v_lshlrev_b32_e32 v15, 4, v6
	v_ashrrev_i32_e32 v23, 31, v22
	v_add_co_u32_e32 v10, vcc, s3, v10
	v_lshl_add_u64 v[26:27], s[10:11], 0, v[24:25]
	v_and_b32_e32 v28, 0x70, v15
	v_mov_b32_e32 v29, v3
	v_lshlrev_b64 v[22:23], 1, v[22:23]
	v_addc_co_u32_e32 v11, vcc, 0, v11, vcc
	s_add_u32 s14, s10, 0x2000
	v_lshl_add_u64 v[26:27], v[26:27], 0, v[28:29]
	v_lshl_add_u64 v[30:31], s[10:11], 0, v[22:23]
	v_add_co_u32_e32 v18, vcc, s3, v18
	s_addc_u32 s15, s11, 0
	v_lshl_add_u64 v[30:31], v[30:31], 0, v[28:29]
	global_load_dwordx4 v[92:95], v[26:27], off
	global_load_dwordx4 v[96:99], v[30:31], off
	v_addc_co_u32_e32 v19, vcc, 0, v19, vcc
	global_load_dwordx4 v[100:103], v[10:11], off
	global_load_dwordx4 v[104:107], v[18:19], off
	v_lshl_add_u64 v[10:11], s[14:15], 0, v[24:25]
	v_lshl_add_u64 v[10:11], v[10:11], 0, v[28:29]
	v_lshl_add_u64 v[18:19], s[14:15], 0, v[22:23]
	v_lshl_add_u64 v[18:19], v[18:19], 0, v[28:29]
	global_load_dwordx4 v[108:111], v[10:11], off
	global_load_dwordx4 v[112:115], v[18:19], off
	s_movk_i32 s3, 0x90
	v_mul_lo_u32 v4, v4, s3
	v_lshl_add_u32 v149, v32, 4, v4
	v_mul_lo_u32 v4, v14, s3
	v_lshl_add_u32 v151, v33, 4, v4
	v_lshrrev_b32_e32 v4, 3, v6
	s_movk_i32 s3, 0x98
	v_mad_u64_u32 v[154:155], s[14:15], v4, s3, v[28:29]
	v_lshrrev_b32_e32 v4, 3, v5
	v_lshlrev_b32_e32 v152, 3, v7
	v_mad_u64_u32 v[156:157], s[14:15], v4, s3, v[28:29]
	v_lshl_add_u64 v[4:5], s[12:13], 0, v[12:13]
	v_lshl_add_u64 v[6:7], s[12:13], 0, v[20:21]
	v_lshl_add_u64 v[4:5], v[4:5], 0, v[8:9]
	s_mov_b64 s[12:13], 0x10000
	v_lshl_add_u64 v[6:7], v[6:7], 0, v[16:17]
	v_lshl_add_u64 v[158:159], v[4:5], 0, s[12:13]
	v_lshl_add_u64 v[160:161], v[6:7], 0, s[12:13]
	s_add_u32 s12, s10, 0x4000
	s_addc_u32 s13, s11, 0
	v_lshl_add_u64 v[8:9], s[12:13], 0, v[24:25]
	s_add_u32 s10, s10, 0x6000
	v_lshl_add_u64 v[162:163], v[8:9], 0, v[28:29]
	v_lshl_add_u64 v[8:9], s[12:13], 0, v[22:23]
	s_mov_b64 s[12:13], 0x18000
	s_addc_u32 s11, s11, 0
	v_lshl_add_u64 v[164:165], v[8:9], 0, v[28:29]
	v_lshlrev_b32_e32 v8, 1, v152
	v_mul_u32_u24_e32 v9, 0x48, v148
	v_lshl_add_u64 v[170:171], v[4:5], 0, s[12:13]
	v_lshl_add_u64 v[4:5], s[10:11], 0, v[24:25]
	v_lshl_add_u32 v153, v9, 1, v8
	v_sub_u32_e32 v8, v8, v152
	v_mul_u32_u24_e32 v9, 0x4c, v148
	v_lshl_add_u64 v[174:175], v[4:5], 0, v[28:29]
	v_lshl_add_u64 v[4:5], s[10:11], 0, v[22:23]
	v_mov_b32_e32 v18, v3
	v_mov_b32_e32 v19, v3
	v_lshl_add_u32 v155, v9, 1, v8
	v_lshl_add_u64 v[172:173], v[6:7], 0, s[12:13]
	v_lshl_add_u64 v[176:177], v[4:5], 0, v[28:29]
	v_mov_b32_e32 v4, v3
	v_mov_b32_e32 v5, v3
	v_mov_b32_e32 v6, v3
	v_mov_b32_e32 v7, v3
	v_mov_b32_e32 v8, v3
	v_mov_b32_e32 v9, v3
	v_mov_b32_e32 v10, v3
	v_mov_b32_e32 v11, v3
	v_mov_b32_e32 v12, v3
	v_mov_b32_e32 v13, v3
	v_mov_b32_e32 v14, v3
	v_mov_b32_e32 v15, v3
	v_mov_b32_e32 v16, v3
	v_mov_b32_e32 v17, v3
	v_mov_b64_e32 v[34:35], v[18:19]
	s_mov_b64 s[10:11], -1
	v_mov_b32_e32 v157, 0
	v_add_u32_e32 v178, 0x2400, v154
	v_add_u32_e32 v179, 0x2400, v156
	v_mov_b64_e32 v[32:33], v[16:17]
	v_mov_b64_e32 v[30:31], v[14:15]
	v_mov_b64_e32 v[28:29], v[12:13]
	v_mov_b64_e32 v[26:27], v[10:11]
	v_mov_b64_e32 v[24:25], v[8:9]
	v_mov_b64_e32 v[22:23], v[6:7]
	v_mov_b64_e32 v[20:21], v[4:5]
	s_mov_b64 s[14:15], -1
	v_mov_b32_e32 v180, 0
	s_branch .LBB0_877
	.p2align	6

; template <int DQK, int MODE> ...
;     ...
;   const int hiw = hi0 + (w >> 1) * dh;
;   const int low = max(0, hiw - span);
;   const int jhi = hi0 + (nw > 2 ? dh : 0);
;   const int jlo = max(0, hi0 - span);
;   const int qpos = qpos0 + 32 * w + ql;
;   if (MODE == 1) {
;     for (int i = tid; i < 513; i += 256) btab[i] = btab_g[i] * LOG2E;
;   }
;   bf16x8 qf[NKK];
;   {
;     const u16* qp = Qp + (long)(32 * w + ql) * qld + hh * 8;
; #pragma unroll
;     for (int kk = 0; kk < NKK; ++kk) {
;       if (active) qf[kk] = *(const bf16x8*)(qp + kk * 16);
;       else qf[kk] = (bf16x8){0, 0, 0, 0, 0, 0, 0, 0};
;     }
;   }
;   struct TRegs { u32x4 k[NKL]; u32x4 v[2]; };
;   auto gload = [&](TRegs& R, int j) {
; #pragma unroll
;     for (int i = 0; i < NKL; ++i) {
;       int c = tid + i * 256;
;       int row = c / KCH, cc = c % KCH;
;       R.k[i] = *(const u32x4*)(Kp + (long)(j * 64 + row) * kld + cc * 8);
;     }
; #pragma unroll
;     for (int i = 0; i < 2; ++i) {
;       int c = tid + i * 256;
;       int d = c >> 3, cc = c & 7;
;       R.v[i] = *(const u32x4*)(VTp + (long)j * 4096 + d * 64 + cc * 8);
;     }
;   };
;   auto lstore = [&](const TRegs& R, int st) {
;     u16* Ks = lds + st * STG;
;     u16* Vs = Ks + KT;
; #pragma unroll
;     for (int i = 0; i < NKL; ++i) {
;       int c = tid + i * 256;
;       int row = c / KCH, cc = c % KCH;
;       *(u32x4*)(Ks + row * KST + cc * 8) = R.k[i];
;     }
; #pragma unroll
;     for (int i = 0; i < 2; ++i) {
;       int c = tid + i * 256;
;       int d = c >> 3, cc = c & 7;
;       u32x2 lo = {R.v[i].x, R.v[i].y}, hi = {R.v[i].z, R.v[i].w};
;       *(u32x2*)(Vs + d * VST + cc * 8) = lo;
;       *(u32x2*)(Vs + d * VST + cc * 8 + 4) = hi;
;     }
;   };
;   f32x16 O[2];
; #pragma unroll
;   for (int du = 0; du < 2; ++du)
; #pragma unroll
;     for (int r = 0; r < 16; ++r) O[du][r] = 0.f;
;   float m_run = 0.f, lsum = 0.f;
;   bool first = true;
;   float carry = active ? 1.f : 0.f;
;   const int dir = (MODE == 2) ? -1 : 1;
;   const int jstart = (MODE == 2) ? jhi : jlo;
;   const int ntile = jhi - jlo + 1;
;     ...
;   {
;     TRegs R0, R1;
;     gload(R0, jstart);
;     if (ntile > 1) gload(R1, jstart + dir);
.LBB0_929:
	v_lshlrev_b32_e32 v156, 3, v5
	v_mov_b32_e32 v49, 0
	s_cmp_lt_i32 s5, -8
	v_mov_b32_e32 v48, 0
	v_mov_b32_e32 v47, 0
	v_mov_b32_e32 v46, 0
	v_mov_b32_e32 v45, 0
	v_mov_b32_e32 v44, 0
	v_mov_b32_e32 v43, 0
	v_mov_b32_e32 v42, 0
	v_mov_b32_e32 v41, 0
	v_mov_b32_e32 v40, 0
	v_mov_b32_e32 v39, 0
	v_mov_b32_e32 v38, 0
	v_mov_b32_e32 v37, 0
	v_mov_b32_e32 v36, 0
	v_mov_b32_e32 v35, 0
	v_mov_b32_e32 v34, 0
	v_mov_b32_e32 v33, 0
	v_mov_b32_e32 v32, 0
	v_mov_b32_e32 v31, 0
	v_mov_b32_e32 v30, 0
	v_mov_b32_e32 v29, 0
	v_mov_b32_e32 v28, 0
	v_mov_b32_e32 v27, 0
	v_mov_b32_e32 v26, 0
	v_mov_b32_e32 v25, 0
	v_mov_b32_e32 v24, 0
	v_mov_b32_e32 v23, 0
	v_mov_b32_e32 v22, 0
	v_mov_b32_e32 v21, 0
	v_mov_b32_e32 v20, 0
	v_mov_b32_e32 v19, 0
	v_mov_b32_e32 v18, 0
	v_mov_b32_e32 v155, 0
	s_cbranch_scc1 .LBB0_958
	v_lshl_add_u64 v[158:159], v[8:9], 1, s[16:17]
	v_ashrrev_i32_e32 v9, 7, v4
	v_cndmask_b32_e64 v9, 0, v9, s[0:1]
	v_add_u32_e32 v157, s3, v9
	v_max_i32_e32 v9, 8, v157
	s_movk_i32 s3, 0x90
	v_add_u32_e32 v174, -8, v9
	v_mul_lo_u32 v9, v151, s3
	v_lshl_add_u32 v175, v8, 1, v9
	v_mul_lo_u32 v8, v153, s3
	v_lshl_add_u32 v176, v12, 1, v8
	v_lshrrev_b32_e32 v8, 3, v4
	s_movk_i32 s3, 0x98
	v_lshl_add_u64 v[160:161], v[12:13], 1, s[16:17]
	s_lshl_b32 s5, s25, 7
	v_mad_u64_u32 v[162:163], s[16:17], v8, s3, v[2:3]
	v_lshrrev_b32_e32 v8, 3, v14
	s_and_b64 s[16:17], exec, s[0:1]
	v_mad_u64_u32 v[164:165], s[16:17], v8, s3, v[2:3]
	v_lshlrev_b32_e32 v2, 1, v156
	v_mul_u32_u24_e32 v8, 0x48, v152
	s_cselect_b32 s15, s5, 0x200
	v_lshl_add_u32 v163, v8, 1, v2
	v_sub_u32_e32 v2, v2, v156
	v_mul_u32_u24_e32 v8, 0x4c, v152
	v_lshl_add_u32 v165, v8, 1, v2
	v_add_u32_e32 v2, s15, v154
	v_add_lshl_u32 v2, v2, v152, 2
	v_sub_u32_e32 v2, v2, v150
	s_lshl_b32 s3, s14, 8
	v_subrev_u32_e32 v2, s3, v2
	s_addk_i32 s15, 0x181
	v_add_u32_e32 v177, 0x9e14, v2
	v_add_u32_e32 v2, s15, v154
	s_lshl_b32 s36, s14, 6
	s_mov_b32 s15, s37
	v_lshlrev_b32_e32 v5, 2, v5
	v_subrev_u32_e32 v179, s36, v2
	s_lshl_b64 s[16:17], s[14:15], 13
	v_and_b32_e32 v2, 7, v4
	v_sub_u32_e32 v178, v152, v5
	v_lshl_or_b32 v4, v2, 4, s16
	v_mov_b32_e32 v5, s17
	v_lshl_add_u64 v[6:7], v[6:7], 1, v[4:5]
	v_lshl_add_u64 v[4:5], v[10:11], 1, v[4:5]
	v_mov_b32_e32 v16, v3
	v_mov_b32_e32 v17, v3
	v_lshl_add_u64 v[170:171], s[10:11], 0, v[6:7]
	v_lshl_add_u64 v[172:173], s[10:11], 0, v[4:5]
	v_mov_b32_e32 v2, v3
	v_mov_b32_e32 v4, v3
	v_mov_b32_e32 v5, v3
	v_mov_b32_e32 v6, v3
	v_mov_b32_e32 v7, v3
	v_mov_b32_e32 v8, v3
	v_mov_b32_e32 v9, v3
	v_mov_b32_e32 v10, v3
	v_mov_b32_e32 v11, v3
	v_mov_b32_e32 v12, v3
	v_mov_b32_e32 v13, v3
	v_mov_b32_e32 v14, v3
	v_mov_b32_e32 v15, v3
	v_mov_b64_e32 v[32:33], v[16:17]
	v_mov_b64_e32 v[48:49], v[16:17]
	s_mov_b32 s5, 3
	s_mov_b64 s[16:17], -1
	v_mov_b32_e32 v155, 0
	s_xor_b64 s[18:19], vcc, -1
	v_mov_b64_e32 v[30:31], v[14:15]
	v_mov_b64_e32 v[28:29], v[12:13]
	v_mov_b64_e32 v[26:27], v[10:11]
	v_mov_b64_e32 v[24:25], v[8:9]
	v_mov_b64_e32 v[22:23], v[6:7]
	v_mov_b64_e32 v[20:21], v[4:5]
	v_mov_b64_e32 v[18:19], v[2:3]
	v_mov_b64_e32 v[46:47], v[14:15]
	v_mov_b64_e32 v[44:45], v[12:13]
	v_mov_b64_e32 v[42:43], v[10:11]
	v_mov_b64_e32 v[40:41], v[8:9]
	v_mov_b64_e32 v[38:39], v[6:7]
	v_mov_b64_e32 v[36:37], v[4:5]
	v_mov_b64_e32 v[34:35], v[2:3]
	v_mov_b32_e32 v2, 0
	s_branch .LBB0_934
	.p2align	6

; template <int DQK, int MODE> ...
;     ...
;       {
;         bf16x8 kf[2][NKK];
; #pragma unroll
;         for (int ku = 0; ku < 2; ++ku)
; #pragma unroll
;           for (int kk = 0; kk < NKK; ++kk)
;             kf[ku][kk] = *(const bf16x8*)(Ks + (ku * 32 + ql) * KST + kk * 16 + hh * 8);
;         __builtin_amdgcn_sched_barrier(0);
; #pragma unroll
;         for (int ku = 0; ku < 2; ++ku)
; #pragma unroll
;           for (int r = 0; r < 16; ++r) S[ku][r] = cinit;
; #pragma unroll
;         for (int kk = 0; kk < NKK; ++kk)
; #pragma unroll
;           for (int ku = 0; ku < 2; ++ku)
;             S[ku] = __builtin_amdgcn_mfma_f32_32x32x16_bf16(kf[ku][kk], qf[kk], S[ku], 0, 0, 0);
;       }
;       u32x4 vf[2][4];
;       if (MODE != 2) {
; #pragma unroll
;         for (int du = 0; du < 2; ++du)
; #pragma unroll
;           for (int s4 = 0; s4 < 4; ++s4) {
;             const u16* vp = Vs + (du * 32 + ql) * VST + 16 * s4 + 4 * hh;
;             u32x2 a = *(const u32x2*)vp;
;             u32x2 b = *(const u32x2*)(vp + 8);
;             vf[du][s4] = (u32x4){a.x, a.y, b.x, b.y};
;           }
;         __builtin_amdgcn_sched_barrier(0);
;       }
;       bf16x8 pf[4];
;       if (MODE != 2) {
;         if (MODE == 1 && !far) {
;           const bool noclip = ((qpos0 + 32 * w + 31) - j * 64 <= 256) && ((qpos0 + 32 * w) - (j * 64 + 63) >= -256);
;           if (noclip) {
;             const float* bt = btab + 256 + qpos - j * 64;
; #pragma unroll
;             for (int ku = 0; ku < 2; ++ku)
; #pragma unroll
;               for (int r = 0; r < 16; ++r) S[ku][r] += bt[-(32 * ku + (r & 3) + 8 * (r >> 2) + 4 * hh)];
;           } else {
; #pragma unroll
;             for (int ku = 0; ku < 2; ++ku)
; #pragma unroll
;               for (int r = 0; r < 16; ++r) {
;                 int key = 32 * ku + (r & 3) + 8 * (r >> 2) + 4 * hh;
;                 int rel = qpos - (j * 64 + key);
;                 rel = min(256, max(-256, rel)) + 256;
;                 S[ku][r] += btab[rel];
;               }
;           }
;         }
;         float mx = -1e30f;
; #pragma unroll
;         for (int ku = 0; ku < 2; ++ku)
; #pragma unroll
;           for (int r = 0; r < 16; ++r) mx = fmaxf(mx, S[ku][r]);
;         if (__builtin_amdgcn_ballot_w64(first || mx > 6.f) != 0ull) {
;           mx = xhalf_max(mx);
;           const float d = first ? mx : (mx > 6.f ? mx : 0.f);
.Lmy_w1_dn:
	v_mfma_f32_32x32x16_bf16 v[66:81], v[8:11], v[82:85], v[66:81]
	s_waitcnt lgkmcnt(9)
	v_mfma_f32_32x32x16_bf16 v[50:65], v[162:165], v[82:85], v[50:65]
	ds_read2_b64 v[162:165], v4 offset0:128 offset1:130
	v_mfma_f32_32x32x16_bf16 v[66:81], v[12:15], v[94:97], v[66:81]
	s_waitcnt lgkmcnt(9)
	v_mfma_f32_32x32x16_bf16 v[50:65], v[204:207], v[94:97], v[50:65]
	v_mfma_f32_32x32x16_bf16 v[66:81], v[146:149], v[90:93], v[66:81]
	s_waitcnt lgkmcnt(8)
	v_mfma_f32_32x32x16_bf16 v[50:65], v[208:211], v[90:93], v[50:65]
	v_mfma_f32_32x32x16_bf16 v[66:81], v[150:153], v[102:105], v[66:81]
	s_waitcnt lgkmcnt(7)
	v_mfma_f32_32x32x16_bf16 v[50:65], v[212:215], v[102:105], v[50:65]
	v_mfma_f32_32x32x16_bf16 v[66:81], v[154:157], v[98:101], v[66:81]
	ds_read2_b64 v[154:157], v4 offset0:132 offset1:134
	ds_read2_b64 v[146:149], v4 offset0:136 offset1:138
	ds_read2_b64 v[8:11], v4 offset0:140 offset1:142
	v_add_u32_e32 v4, 0x4000, v187
	ds_read2_b64 v[158:161], v4 offset0:224 offset1:226
	ds_read2_b64 v[150:153], v4 offset0:228 offset1:230
	ds_read2_b64 v[12:15], v4 offset0:232 offset1:234
	ds_read2_b64 v[4:7], v4 offset0:236 offset1:238
	s_waitcnt lgkmcnt(13)
	v_mfma_f32_32x32x16_bf16 v[50:65], v[216:219], v[98:101], v[50:65]
	s_nop 1
	v_max3_f32 v16, v66, s38, v67
	v_max3_f32 v16, v16, v68, v69
	v_max3_f32 v16, v16, v70, v71
	v_max3_f32 v16, v16, v72, v73
	v_max3_f32 v16, v16, v74, v75
	v_max3_f32 v16, v16, v76, v77
	v_max3_f32 v16, v16, v78, v79
	v_max3_f32 v16, v16, v80, v81
	s_nop 1
	v_max3_f32 v16, v16, v50, v51
	v_max3_f32 v16, v16, v52, v53
	v_max3_f32 v16, v16, v54, v55
	v_max3_f32 v16, v16, v56, v57
	v_max3_f32 v16, v16, v58, v59
	v_max3_f32 v16, v16, v60, v61
	v_max3_f32 v16, v16, v62, v63
	v_max3_f32 v16, v16, v64, v65
	v_cmp_lt_f32_e32 vcc, s39, v16
	s_or_b64 vcc, s[0:1], vcc
	s_cbranch_vccz .LBB0_995
	v_mov_b32_e32 v17, v16
	s_nop 1
	v_permlane32_swap_b32_e32 v16, v17
	v_max_f32_e32 v17, v17, v17
	v_max_f32_e32 v16, v16, v16
	v_max_f32_e32 v16, v16, v17
	v_cmp_lt_f32_e32 vcc, s39, v16
	s_or_b64 vcc, s[0:1], vcc
	s_nop 0
	v_cndmask_b32_e32 v16, 0, v16, vcc
	v_exp_f32_e64 v17, -v16
	v_add_f32_e32 v2, v2, v16
	v_sub_f32_e32 v228, 0, v2
	v_mov_b32_e32 v229, v228
	v_mov_b32_e32 v230, v228
	v_mov_b32_e32 v231, v228
	v_mov_b32_e32 v232, v228
	v_mov_b32_e32 v233, v228
	v_mov_b32_e32 v234, v228
	v_mov_b32_e32 v235, v228
	v_mov_b32_e32 v236, v228
	v_mov_b32_e32 v237, v228
	v_mov_b32_e32 v238, v228
	v_mov_b32_e32 v239, v228
	v_mov_b32_e32 v240, v228
	v_mov_b32_e32 v241, v228
	v_mov_b32_e32 v242, v228
	v_mov_b32_e32 v243, v228
	v_cndmask_b32_e64 v204, v17, 1.0, s[0:1]
	v_mul_f32_e32 v177, v177, v204
	v_pk_add_f32 v[66:67], v[66:67], v[16:17] op_sel_hi:[1,0] neg_lo:[0,1] neg_hi:[0,1]
	v_pk_add_f32 v[68:69], v[68:69], v[16:17] op_sel_hi:[1,0] neg_lo:[0,1] neg_hi:[0,1]
	v_pk_add_f32 v[70:71], v[70:71], v[16:17] op_sel_hi:[1,0] neg_lo:[0,1] neg_hi:[0,1]
	v_pk_add_f32 v[72:73], v[72:73], v[16:17] op_sel_hi:[1,0] neg_lo:[0,1] neg_hi:[0,1]
	v_pk_add_f32 v[74:75], v[74:75], v[16:17] op_sel_hi:[1,0] neg_lo:[0,1] neg_hi:[0,1]
	v_pk_add_f32 v[76:77], v[76:77], v[16:17] op_sel_hi:[1,0] neg_lo:[0,1] neg_hi:[0,1]
	v_pk_add_f32 v[78:79], v[78:79], v[16:17] op_sel_hi:[1,0] neg_lo:[0,1] neg_hi:[0,1]
	v_pk_add_f32 v[80:81], v[80:81], v[16:17] op_sel_hi:[1,0] neg_lo:[0,1] neg_hi:[0,1]
	v_pk_add_f32 v[50:51], v[50:51], v[16:17] op_sel_hi:[1,0] neg_lo:[0,1] neg_hi:[0,1]
	v_pk_add_f32 v[52:53], v[52:53], v[16:17] op_sel_hi:[1,0] neg_lo:[0,1] neg_hi:[0,1]
	v_pk_add_f32 v[54:55], v[54:55], v[16:17] op_sel_hi:[1,0] neg_lo:[0,1] neg_hi:[0,1]
	v_pk_add_f32 v[56:57], v[56:57], v[16:17] op_sel_hi:[1,0] neg_lo:[0,1] neg_hi:[0,1]
	v_pk_add_f32 v[58:59], v[58:59], v[16:17] op_sel_hi:[1,0] neg_lo:[0,1] neg_hi:[0,1]
	v_pk_add_f32 v[60:61], v[60:61], v[16:17] op_sel_hi:[1,0] neg_lo:[0,1] neg_hi:[0,1]
	v_pk_add_f32 v[62:63], v[62:63], v[16:17] op_sel_hi:[1,0] neg_lo:[0,1] neg_hi:[0,1]
	v_pk_add_f32 v[64:65], v[64:65], v[16:17] op_sel_hi:[1,0] neg_lo:[0,1] neg_hi:[0,1]
	v_pk_mul_f32 v[48:49], v[48:49], v[204:205] op_sel_hi:[1,0]
	v_pk_mul_f32 v[46:47], v[46:47], v[204:205] op_sel_hi:[1,0]
	v_pk_mul_f32 v[44:45], v[44:45], v[204:205] op_sel_hi:[1,0]
	v_pk_mul_f32 v[42:43], v[42:43], v[204:205] op_sel_hi:[1,0]
	v_pk_mul_f32 v[40:41], v[40:41], v[204:205] op_sel_hi:[1,0]
	v_pk_mul_f32 v[38:39], v[38:39], v[204:205] op_sel_hi:[1,0]
	v_pk_mul_f32 v[36:37], v[36:37], v[204:205] op_sel_hi:[1,0]
	v_pk_mul_f32 v[34:35], v[34:35], v[204:205] op_sel_hi:[1,0]
	v_pk_mul_f32 v[32:33], v[32:33], v[204:205] op_sel_hi:[1,0]
	v_pk_mul_f32 v[30:31], v[30:31], v[204:205] op_sel_hi:[1,0]
	v_pk_mul_f32 v[28:29], v[28:29], v[204:205] op_sel_hi:[1,0]
	v_pk_mul_f32 v[26:27], v[26:27], v[204:205] op_sel_hi:[1,0]
	v_pk_mul_f32 v[24:25], v[24:25], v[204:205] op_sel_hi:[1,0]
	v_pk_mul_f32 v[22:23], v[22:23], v[204:205] op_sel_hi:[1,0]
	v_pk_mul_f32 v[20:21], v[20:21], v[204:205] op_sel_hi:[1,0]
	v_pk_mul_f32 v[18:19], v[18:19], v[204:205] op_sel_hi:[1,0]
	.p2align	6

; template <int DQK, int MODE> ...
;     ...
;   struct TRegs { u32x4 k[NKL]; u32x4 v[2]; };
;   auto gload = [&](TRegs& R, int j) {
; #pragma unroll
;     for (int i = 0; i < NKL; ++i) {
;       int c = tid + i * 256;
;       int row = c / KCH, cc = c % KCH;
;       R.k[i] = *(const u32x4*)(Kp + (long)(j * 64 + row) * kld + cc * 8);
;     }
; #pragma unroll
;     for (int i = 0; i < 2; ++i) {
;       int c = tid + i * 256;
;       int d = c >> 3, cc = c & 7;
;       R.v[i] = *(const u32x4*)(VTp + (long)j * 4096 + d * 64 + cc * 8);
;     }
;   };
;   auto lstore = [&](const TRegs& R, int st) {
;     u16* Ks = lds + st * STG;
;     u16* Vs = Ks + KT;
; #pragma unroll
;     for (int i = 0; i < NKL; ++i) {
;       int c = tid + i * 256;
;       int row = c / KCH, cc = c % KCH;
;       *(u32x4*)(Ks + row * KST + cc * 8) = R.k[i];
;     }
; #pragma unroll
;     for (int i = 0; i < 2; ++i) {
;       int c = tid + i * 256;
;       int d = c >> 3, cc = c & 7;
;       u32x2 lo = {R.v[i].x, R.v[i].y}, hi = {R.v[i].z, R.v[i].w};
;       *(u32x2*)(Vs + d * VST + cc * 8) = lo;
;       *(u32x2*)(Vs + d * VST + cc * 8 + 4) = hi;
;     }
;   };
;   f32x16 O[2];
; #pragma unroll
;   for (int du = 0; du < 2; ++du)
; #pragma unroll
;     for (int r = 0; r < 16; ++r) O[du][r] = 0.f;
;   float m_run = 0.f, lsum = 0.f;
;   bool first = true;
;   float carry = active ? 1.f : 0.f;
;   const int dir = (MODE == 2) ? -1 : 1;
;   const int jstart = (MODE == 2) ? jhi : jlo;
;   const int ntile = jhi - jlo + 1;
;     ...
;   {
;     TRegs R0, R1;
;     gload(R0, jstart);
;     if (ntile > 1) gload(R1, jstart + dir);
.LBB0_2011:
	s_or_b64 exec, exec, s[2:3]
	v_ashrrev_i32_e32 v2, 31, v4
	v_lshrrev_b32_e32 v2, 29, v2
	v_add_u32_e32 v3, v4, v2
	s_add_i32 s9, s39, 2
	v_ashrrev_i32_e32 v2, 3, v3
	v_and_b32_e32 v3, -8, v3
	s_and_b64 s[2:3], exec, s[46:47]
	v_sub_u32_e32 v30, v4, v3
	v_ashrrev_i32_e32 v3, 31, v2
	s_cselect_b32 s2, s42, s9
	v_readlane_b32 s68, v253, 38
	v_lshlrev_b64 v[6:7], 9, v[2:3]
	v_add_u32_e32 v3, 0x100, v4
	s_ashr_i32 s3, s2, 31
	v_readlane_b32 s69, v253, 39
	v_ashrrev_i32_e32 v12, 31, v3
	s_lshl_b64 s[2:3], s[2:3], 17
	v_readlane_b32 s70, v253, 40
	v_readlane_b32 s71, v253, 41
	v_readlane_b32 s72, v253, 42
	v_readlane_b32 s73, v253, 43
	s_mov_b64 s[12:13], s[68:69]
	v_lshrrev_b32_e32 v12, 29, v12
	s_add_u32 s9, s12, s2
	v_add_u32_e32 v13, v3, v12
	s_addc_u32 s10, s13, s3
	v_ashrrev_i32_e32 v12, 3, v13
	v_and_b32_e32 v13, -8, v13
	s_add_u32 s8, s9, s8
	v_sub_u32_e32 v31, v3, v13
	v_ashrrev_i32_e32 v13, 31, v12
	s_mov_b64 s[14:15], s[70:71]
	s_addc_u32 s9, s10, 0
	v_lshlrev_b32_e32 v10, 3, v30
	v_lshlrev_b64 v[14:15], 9, v[12:13]
	v_lshlrev_b32_e32 v13, 3, v4
	s_add_u32 s2, s14, s2
	v_ashrrev_i32_e32 v11, 31, v10
	v_lshlrev_b32_e32 v18, 3, v31
	v_and_b32_e32 v20, 0xffffffc0, v13
	s_addc_u32 s3, s15, s3
	s_lshl_b32 s10, s43, 15
	v_lshl_add_u64 v[8:9], s[8:9], 0, v[6:7]
	v_lshlrev_b64 v[10:11], 1, v[10:11]
	v_ashrrev_i32_e32 v19, 31, v18
	v_ashrrev_i32_e32 v21, 31, v20
	s_add_u32 s2, s2, s10
	v_lshl_add_u64 v[8:9], v[8:9], 0, v[10:11]
	v_lshl_add_u64 v[16:17], s[8:9], 0, v[14:15]
	v_lshlrev_b64 v[18:19], 1, v[18:19]
	v_lshlrev_b64 v[22:23], 1, v[20:21]
	v_add_u32_e32 v20, 0x800, v20
	s_addc_u32 s3, s3, 0
	v_lshl_add_u64 v[16:17], v[16:17], 0, v[18:19]
	global_load_dwordx4 v[82:85], v[8:9], off
	global_load_dwordx4 v[86:89], v[16:17], off
	v_lshlrev_b32_e32 v13, 4, v4
	v_ashrrev_i32_e32 v21, 31, v20
	v_add_co_u32_e32 v8, vcc, s94, v8
	v_lshl_add_u64 v[24:25], s[2:3], 0, v[22:23]
	v_and_b32_e32 v26, 0x70, v13
	v_mov_b32_e32 v27, v1
	v_lshlrev_b64 v[20:21], 1, v[20:21]
	v_addc_co_u32_e32 v9, vcc, 0, v9, vcc
	s_add_u32 s10, s2, 0x2000
	v_lshl_add_u64 v[24:25], v[24:25], 0, v[26:27]
	v_lshl_add_u64 v[28:29], s[2:3], 0, v[20:21]
	v_add_co_u32_e32 v16, vcc, s94, v16
	s_addc_u32 s11, s3, 0
	v_lshl_add_u64 v[28:29], v[28:29], 0, v[26:27]
	global_load_dwordx4 v[90:93], v[24:25], off
	global_load_dwordx4 v[94:97], v[28:29], off
	v_addc_co_u32_e32 v17, vcc, 0, v17, vcc
	global_load_dwordx4 v[98:101], v[8:9], off
	global_load_dwordx4 v[102:105], v[16:17], off
	v_lshl_add_u64 v[8:9], s[10:11], 0, v[22:23]
	v_lshl_add_u64 v[8:9], v[8:9], 0, v[26:27]
	v_lshl_add_u64 v[16:17], s[10:11], 0, v[20:21]
	v_lshl_add_u64 v[16:17], v[16:17], 0, v[26:27]
	global_load_dwordx4 v[106:109], v[8:9], off
	global_load_dwordx4 v[110:113], v[16:17], off
	s_movk_i32 s10, 0x90
	v_mul_lo_u32 v2, v2, s10
	v_lshl_add_u32 v147, v30, 4, v2
	v_mul_lo_u32 v2, v12, s10
	v_lshl_add_u32 v149, v31, 4, v2
	v_lshrrev_b32_e32 v2, 3, v4
	v_mad_u64_u32 v[152:153], s[10:11], v2, s95, v[26:27]
	v_lshrrev_b32_e32 v2, 3, v3
	v_lshlrev_b32_e32 v150, 3, v5
	v_mad_u64_u32 v[154:155], s[10:11], v2, s95, v[26:27]
	v_lshl_add_u64 v[2:3], s[8:9], 0, v[10:11]
	v_lshl_add_u64 v[4:5], s[8:9], 0, v[18:19]
	v_lshl_add_u64 v[2:3], v[2:3], 0, v[6:7]
	s_mov_b64 s[8:9], 0x10000
	v_lshl_add_u64 v[4:5], v[4:5], 0, v[14:15]
	v_lshl_add_u64 v[156:157], v[2:3], 0, s[8:9]
	v_lshl_add_u64 v[158:159], v[4:5], 0, s[8:9]
	s_add_u32 s8, s2, 0x4000
	s_addc_u32 s9, s3, 0
	v_lshl_add_u64 v[6:7], s[8:9], 0, v[22:23]
	s_add_u32 s2, s2, 0x6000
	v_lshl_add_u64 v[160:161], v[6:7], 0, v[26:27]
	v_lshl_add_u64 v[6:7], s[8:9], 0, v[20:21]
	s_mov_b64 s[8:9], 0x18000
	s_addc_u32 s3, s3, 0
	v_lshl_add_u64 v[162:163], v[6:7], 0, v[26:27]
	v_lshlrev_b32_e32 v6, 1, v150
	v_mul_u32_u24_e32 v7, 0x48, v146
	v_lshl_add_u64 v[168:169], v[2:3], 0, s[8:9]
	v_lshl_add_u64 v[2:3], s[2:3], 0, v[22:23]
	v_lshl_add_u32 v151, v7, 1, v6
	v_sub_u32_e32 v6, v6, v150
	v_mul_u32_u24_e32 v7, 0x4c, v146
	v_lshl_add_u64 v[172:173], v[2:3], 0, v[26:27]
	v_lshl_add_u64 v[2:3], s[2:3], 0, v[20:21]
	v_mov_b32_e32 v16, v1
	v_mov_b32_e32 v17, v1
	v_lshl_add_u32 v153, v7, 1, v6
	v_lshl_add_u64 v[170:171], v[4:5], 0, s[8:9]
	v_lshl_add_u64 v[174:175], v[2:3], 0, v[26:27]
	v_mov_b32_e32 v2, v1
	v_mov_b32_e32 v3, v1
	v_mov_b32_e32 v4, v1
	v_mov_b32_e32 v5, v1
	v_mov_b32_e32 v6, v1
	v_mov_b32_e32 v7, v1
	v_mov_b32_e32 v8, v1
	v_mov_b32_e32 v9, v1
	v_mov_b32_e32 v10, v1
	v_mov_b32_e32 v11, v1
	v_mov_b32_e32 v12, v1
	v_mov_b32_e32 v13, v1
	v_mov_b32_e32 v14, v1
	v_mov_b32_e32 v15, v1
	v_mov_b64_e32 v[32:33], v[16:17]
	s_mov_b64 s[2:3], -1
	v_mov_b32_e32 v155, 0
	v_add_u32_e32 v176, 0x2400, v152
	v_add_u32_e32 v177, 0x2400, v154
	v_mov_b64_e32 v[30:31], v[14:15]
	v_mov_b64_e32 v[28:29], v[12:13]
	v_mov_b64_e32 v[26:27], v[10:11]
	v_mov_b64_e32 v[24:25], v[8:9]
	v_mov_b64_e32 v[22:23], v[6:7]
	v_mov_b64_e32 v[20:21], v[4:5]
	v_mov_b64_e32 v[18:19], v[2:3]
	s_mov_b64 s[10:11], -1
	v_mov_b32_e32 v178, 0
	v_readlane_b32 s74, v253, 44
	v_readlane_b32 s75, v253, 45
	s_mov_b64 s[16:17], s[72:73]
	s_branch .LBB0_2014
	.p2align	6

; template <int DQK, int MODE> ...
;     ...
;   const int hiw = hi0 + (w >> 1) * dh;
;   const int low = max(0, hiw - span);
;   const int jhi = hi0 + (nw > 2 ? dh : 0);
;   const int jlo = max(0, hi0 - span);
;   const int qpos = qpos0 + 32 * w + ql;
;   if (MODE == 1) {
;     for (int i = tid; i < 513; i += 256) btab[i] = btab_g[i] * LOG2E;
;   }
;   bf16x8 qf[NKK];
;   {
;     const u16* qp = Qp + (long)(32 * w + ql) * qld + hh * 8;
; #pragma unroll
;     for (int kk = 0; kk < NKK; ++kk) {
;       if (active) qf[kk] = *(const bf16x8*)(qp + kk * 16);
;       else qf[kk] = (bf16x8){0, 0, 0, 0, 0, 0, 0, 0};
;     }
;   }
;   struct TRegs { u32x4 k[NKL]; u32x4 v[2]; };
;   auto gload = [&](TRegs& R, int j) {
; #pragma unroll
;     for (int i = 0; i < NKL; ++i) {
;       int c = tid + i * 256;
;       int row = c / KCH, cc = c % KCH;
;       R.k[i] = *(const u32x4*)(Kp + (long)(j * 64 + row) * kld + cc * 8);
;     }
; #pragma unroll
;     for (int i = 0; i < 2; ++i) {
;       int c = tid + i * 256;
;       int d = c >> 3, cc = c & 7;
;       R.v[i] = *(const u32x4*)(VTp + (long)j * 4096 + d * 64 + cc * 8);
;     }
;   };
;   auto lstore = [&](const TRegs& R, int st) {
;     u16* Ks = lds + st * STG;
;     u16* Vs = Ks + KT;
; #pragma unroll
;     for (int i = 0; i < NKL; ++i) {
;       int c = tid + i * 256;
;       int row = c / KCH, cc = c % KCH;
;       *(u32x4*)(Ks + row * KST + cc * 8) = R.k[i];
;     }
; #pragma unroll
;     for (int i = 0; i < 2; ++i) {
;       int c = tid + i * 256;
;       int d = c >> 3, cc = c & 7;
;       u32x2 lo = {R.v[i].x, R.v[i].y}, hi = {R.v[i].z, R.v[i].w};
;       *(u32x2*)(Vs + d * VST + cc * 8) = lo;
;       *(u32x2*)(Vs + d * VST + cc * 8 + 4) = hi;
;     }
;   };
;   f32x16 O[2];
; #pragma unroll
;   for (int du = 0; du < 2; ++du)
; #pragma unroll
;     for (int r = 0; r < 16; ++r) O[du][r] = 0.f;
;   float m_run = 0.f, lsum = 0.f;
;   bool first = true;
;   float carry = active ? 1.f : 0.f;
;   const int dir = (MODE == 2) ? -1 : 1;
;   const int jstart = (MODE == 2) ? jhi : jlo;
;   const int ntile = jhi - jlo + 1;
;     ...
;   {
;     TRegs R0, R1;
;     gload(R0, jstart);
;     if (ntile > 1) gload(R1, jstart + dir);
.LBB0_2066:
	v_lshlrev_b32_e32 v154, 3, v3
	v_mov_b32_e32 v47, 0
	s_cmp_lt_i32 s14, -8
	v_mov_b32_e32 v46, 0
	v_mov_b32_e32 v45, 0
	v_mov_b32_e32 v44, 0
	v_mov_b32_e32 v43, 0
	v_mov_b32_e32 v42, 0
	v_mov_b32_e32 v41, 0
	v_mov_b32_e32 v40, 0
	v_mov_b32_e32 v39, 0
	v_mov_b32_e32 v38, 0
	v_mov_b32_e32 v37, 0
	v_mov_b32_e32 v36, 0
	v_mov_b32_e32 v35, 0
	v_mov_b32_e32 v34, 0
	v_mov_b32_e32 v33, 0
	v_mov_b32_e32 v32, 0
	v_mov_b32_e32 v31, 0
	v_mov_b32_e32 v30, 0
	v_mov_b32_e32 v29, 0
	v_mov_b32_e32 v28, 0
	v_mov_b32_e32 v27, 0
	v_mov_b32_e32 v26, 0
	v_mov_b32_e32 v25, 0
	v_mov_b32_e32 v24, 0
	v_mov_b32_e32 v23, 0
	v_mov_b32_e32 v22, 0
	v_mov_b32_e32 v21, 0
	v_mov_b32_e32 v20, 0
	v_mov_b32_e32 v19, 0
	v_mov_b32_e32 v18, 0
	v_mov_b32_e32 v17, 0
	v_mov_b32_e32 v16, 0
	v_mov_b32_e32 v153, 0
	s_cbranch_scc1 .LBB0_2095
	v_lshl_add_u64 v[156:157], v[6:7], 1, s[12:13]
	v_ashrrev_i32_e32 v7, 7, v2
	v_cndmask_b32_e64 v7, 0, v7, s[46:47]
	v_add_u32_e32 v155, s11, v7
	v_max_i32_e32 v7, 8, v155
	s_movk_i32 s11, 0x90
	v_add_u32_e32 v172, -8, v7
	v_mul_lo_u32 v7, v149, s11
	v_lshl_add_u32 v173, v6, 1, v7
	v_mul_lo_u32 v6, v151, s11
	v_lshl_add_u32 v174, v10, 1, v6
	v_lshrrev_b32_e32 v6, 3, v2
	v_lshl_add_u64 v[158:159], v[10:11], 1, s[12:13]
	s_lshl_b32 s14, s92, 7
	v_mad_u64_u32 v[160:161], s[12:13], v6, s95, v[0:1]
	v_lshrrev_b32_e32 v6, 3, v12
	s_and_b64 s[12:13], exec, s[46:47]
	v_mad_u64_u32 v[162:163], s[12:13], v6, s95, v[0:1]
	v_lshlrev_b32_e32 v0, 1, v154
	v_mul_u32_u24_e32 v6, 0x48, v150
	s_cselect_b32 s14, s14, 0x200
	v_lshl_add_u32 v161, v6, 1, v0
	v_sub_u32_e32 v0, v0, v154
	v_mul_u32_u24_e32 v6, 0x4c, v150
	v_lshl_add_u32 v163, v6, 1, v0
	v_add_u32_e32 v0, s14, v152
	v_add_lshl_u32 v0, v0, v150, 2
	v_sub_u32_e32 v0, v0, v148
	s_lshl_b32 s11, s10, 8
	v_subrev_u32_e32 v0, s11, v0
	s_addk_i32 s14, 0x181
	v_add_u32_e32 v175, 0x9e14, v0
	v_add_u32_e32 v0, s14, v152
	s_lshl_b32 s31, s10, 6
	s_mov_b32 s11, s19
	v_lshlrev_b32_e32 v3, 2, v3
	v_subrev_u32_e32 v177, s31, v0
	s_lshl_b64 s[12:13], s[10:11], 13
	v_and_b32_e32 v0, 7, v2
	v_sub_u32_e32 v176, v150, v3
	v_lshl_or_b32 v2, v0, 4, s12
	v_mov_b32_e32 v3, s13
	v_lshl_add_u64 v[4:5], v[4:5], 1, v[2:3]
	v_lshl_add_u64 v[2:3], v[8:9], 1, v[2:3]
	v_mov_b32_e32 v14, v1
	v_mov_b32_e32 v15, v1
	v_lshl_add_u64 v[168:169], s[2:3], 0, v[4:5]
	v_lshl_add_u64 v[170:171], s[2:3], 0, v[2:3]
	v_mov_b32_e32 v0, v1
	v_mov_b32_e32 v2, v1
	v_mov_b32_e32 v3, v1
	v_mov_b32_e32 v4, v1
	v_mov_b32_e32 v5, v1
	v_mov_b32_e32 v6, v1
	v_mov_b32_e32 v7, v1
	v_mov_b32_e32 v8, v1
	v_mov_b32_e32 v9, v1
	v_mov_b32_e32 v10, v1
	v_mov_b32_e32 v11, v1
	v_mov_b32_e32 v12, v1
	v_mov_b32_e32 v13, v1
	v_mov_b64_e32 v[30:31], v[14:15]
	v_mov_b64_e32 v[46:47], v[14:15]
	s_mov_b32 s18, 3
	s_mov_b64 s[12:13], -1
	v_mov_b32_e32 v153, 0
	s_xor_b64 s[14:15], vcc, -1
	v_mov_b64_e32 v[28:29], v[12:13]
	v_mov_b64_e32 v[26:27], v[10:11]
	v_mov_b64_e32 v[24:25], v[8:9]
	v_mov_b64_e32 v[22:23], v[6:7]
	v_mov_b64_e32 v[20:21], v[4:5]
	v_mov_b64_e32 v[18:19], v[2:3]
	v_mov_b64_e32 v[16:17], v[0:1]
	v_mov_b64_e32 v[44:45], v[12:13]
	v_mov_b64_e32 v[42:43], v[10:11]
	v_mov_b64_e32 v[40:41], v[8:9]
	v_mov_b64_e32 v[38:39], v[6:7]
	v_mov_b64_e32 v[36:37], v[4:5]
	v_mov_b64_e32 v[34:35], v[2:3]
	v_mov_b64_e32 v[32:33], v[0:1]
	v_mov_b32_e32 v0, 0
	s_branch .LBB0_2071
	.p2align	6

; template <int DQK, int MODE> ...
;     ...
;       {
;         bf16x8 kf[2][NKK];
; #pragma unroll
;         for (int ku = 0; ku < 2; ++ku)
; #pragma unroll
;           for (int kk = 0; kk < NKK; ++kk)
;             kf[ku][kk] = *(const bf16x8*)(Ks + (ku * 32 + ql) * KST + kk * 16 + hh * 8);
;         __builtin_amdgcn_sched_barrier(0);
; #pragma unroll
;         for (int ku = 0; ku < 2; ++ku)
; #pragma unroll
;           for (int r = 0; r < 16; ++r) S[ku][r] = cinit;
; #pragma unroll
;         for (int kk = 0; kk < NKK; ++kk)
; #pragma unroll
;           for (int ku = 0; ku < 2; ++ku)
;             S[ku] = __builtin_amdgcn_mfma_f32_32x32x16_bf16(kf[ku][kk], qf[kk], S[ku], 0, 0, 0);
;       }
;       u32x4 vf[2][4];
;       if (MODE != 2) {
; #pragma unroll
;         for (int du = 0; du < 2; ++du)
; #pragma unroll
;           for (int s4 = 0; s4 < 4; ++s4) {
;             const u16* vp = Vs + (du * 32 + ql) * VST + 16 * s4 + 4 * hh;
;             u32x2 a = *(const u32x2*)vp;
;             u32x2 b = *(const u32x2*)(vp + 8);
;             vf[du][s4] = (u32x4){a.x, a.y, b.x, b.y};
;           }
;         __builtin_amdgcn_sched_barrier(0);
;       }
;       bf16x8 pf[4];
;       if (MODE != 2) {
;         if (MODE == 1 && !far) {
;           const bool noclip = ((qpos0 + 32 * w + 31) - j * 64 <= 256) && ((qpos0 + 32 * w) - (j * 64 + 63) >= -256);
;           if (noclip) {
;             const float* bt = btab + 256 + qpos - j * 64;
; #pragma unroll
;             for (int ku = 0; ku < 2; ++ku)
; #pragma unroll
;               for (int r = 0; r < 16; ++r) S[ku][r] += bt[-(32 * ku + (r & 3) + 8 * (r >> 2) + 4 * hh)];
;           } else {
; #pragma unroll
;             for (int ku = 0; ku < 2; ++ku)
; #pragma unroll
;               for (int r = 0; r < 16; ++r) {
;                 int key = 32 * ku + (r & 3) + 8 * (r >> 2) + 4 * hh;
;                 int rel = qpos - (j * 64 + key);
;                 rel = min(256, max(-256, rel)) + 256;
;                 S[ku][r] += btab[rel];
;               }
;           }
;         }
;         float mx = -1e30f;
; #pragma unroll
;         for (int ku = 0; ku < 2; ++ku)
; #pragma unroll
;           for (int r = 0; r < 16; ++r) mx = fmaxf(mx, S[ku][r]);
;         if (__builtin_amdgcn_ballot_w64(first || mx > 6.f) != 0ull) {
;           mx = xhalf_max(mx);
;           const float d = first ? mx : (mx > 6.f ? mx : 0.f);
.Lmy_w5_dn:
	v_mfma_f32_32x32x16_bf16 v[64:79], v[6:9], v[80:83], v[64:79]
	s_waitcnt lgkmcnt(9)
	v_mfma_f32_32x32x16_bf16 v[48:63], v[160:163], v[80:83], v[48:63]
	ds_read2_b64 v[160:163], v2 offset0:128 offset1:130
	v_mfma_f32_32x32x16_bf16 v[64:79], v[10:13], v[92:95], v[64:79]
	s_waitcnt lgkmcnt(9)
	v_mfma_f32_32x32x16_bf16 v[48:63], v[204:207], v[92:95], v[48:63]
	v_mfma_f32_32x32x16_bf16 v[64:79], v[144:147], v[88:91], v[64:79]
	s_waitcnt lgkmcnt(8)
	v_mfma_f32_32x32x16_bf16 v[48:63], v[208:211], v[88:91], v[48:63]
	v_mfma_f32_32x32x16_bf16 v[64:79], v[148:151], v[100:103], v[64:79]
	s_waitcnt lgkmcnt(7)
	v_mfma_f32_32x32x16_bf16 v[48:63], v[212:215], v[100:103], v[48:63]
	v_mfma_f32_32x32x16_bf16 v[64:79], v[152:155], v[96:99], v[64:79]
	ds_read2_b64 v[152:155], v2 offset0:132 offset1:134
	ds_read2_b64 v[144:147], v2 offset0:136 offset1:138
	ds_read2_b64 v[6:9], v2 offset0:140 offset1:142
	v_add_u32_e32 v2, 0x4000, v185
	ds_read2_b64 v[156:159], v2 offset0:224 offset1:226
	ds_read2_b64 v[148:151], v2 offset0:228 offset1:230
	ds_read2_b64 v[10:13], v2 offset0:232 offset1:234
	ds_read2_b64 v[2:5], v2 offset0:236 offset1:238
	s_waitcnt lgkmcnt(13)
	v_mfma_f32_32x32x16_bf16 v[48:63], v[216:219], v[96:99], v[48:63]
	s_nop 1
	v_max3_f32 v14, v64, s96, v65
	v_max3_f32 v14, v14, v66, v67
	v_max3_f32 v14, v14, v68, v69
	v_max3_f32 v14, v14, v70, v71
	v_max3_f32 v14, v14, v72, v73
	v_max3_f32 v14, v14, v74, v75
	v_max3_f32 v14, v14, v76, v77
	v_max3_f32 v14, v14, v78, v79
	s_nop 1
	v_max3_f32 v14, v14, v48, v49
	v_max3_f32 v14, v14, v50, v51
	v_max3_f32 v14, v14, v52, v53
	v_max3_f32 v14, v14, v54, v55
	v_max3_f32 v14, v14, v56, v57
	v_max3_f32 v14, v14, v58, v59
	v_max3_f32 v14, v14, v60, v61
	v_max3_f32 v14, v14, v62, v63
	v_cmp_lt_f32_e32 vcc, s97, v14
	s_or_b64 vcc, s[10:11], vcc
	s_cbranch_vccz .LBB0_2132
	v_mov_b32_e32 v15, v14
	s_nop 1
	v_permlane32_swap_b32_e32 v14, v15
	v_max_f32_e32 v15, v15, v15
	v_max_f32_e32 v14, v14, v14
	v_max_f32_e32 v14, v14, v15
	v_cmp_lt_f32_e32 vcc, s97, v14
	s_or_b64 vcc, s[10:11], vcc
	s_nop 0
	v_cndmask_b32_e32 v14, 0, v14, vcc
	v_exp_f32_e64 v15, -v14
	v_add_f32_e32 v0, v0, v14
	v_sub_f32_e32 v228, 0, v0
	v_mov_b32_e32 v229, v228
	v_mov_b32_e32 v230, v228
	v_mov_b32_e32 v231, v228
	v_mov_b32_e32 v232, v228
	v_mov_b32_e32 v233, v228
	v_mov_b32_e32 v234, v228
	v_mov_b32_e32 v235, v228
	v_mov_b32_e32 v236, v228
	v_mov_b32_e32 v237, v228
	v_mov_b32_e32 v238, v228
	v_mov_b32_e32 v239, v228
	v_mov_b32_e32 v240, v228
	v_mov_b32_e32 v241, v228
	v_mov_b32_e32 v242, v228
	v_mov_b32_e32 v243, v228
	v_cndmask_b32_e64 v204, v15, 1.0, s[10:11]
	v_mul_f32_e32 v175, v175, v204
	v_pk_add_f32 v[64:65], v[64:65], v[14:15] op_sel_hi:[1,0] neg_lo:[0,1] neg_hi:[0,1]
	v_pk_add_f32 v[66:67], v[66:67], v[14:15] op_sel_hi:[1,0] neg_lo:[0,1] neg_hi:[0,1]
	v_pk_add_f32 v[68:69], v[68:69], v[14:15] op_sel_hi:[1,0] neg_lo:[0,1] neg_hi:[0,1]
	v_pk_add_f32 v[70:71], v[70:71], v[14:15] op_sel_hi:[1,0] neg_lo:[0,1] neg_hi:[0,1]
	v_pk_add_f32 v[72:73], v[72:73], v[14:15] op_sel_hi:[1,0] neg_lo:[0,1] neg_hi:[0,1]
	v_pk_add_f32 v[74:75], v[74:75], v[14:15] op_sel_hi:[1,0] neg_lo:[0,1] neg_hi:[0,1]
	v_pk_add_f32 v[76:77], v[76:77], v[14:15] op_sel_hi:[1,0] neg_lo:[0,1] neg_hi:[0,1]
	v_pk_add_f32 v[78:79], v[78:79], v[14:15] op_sel_hi:[1,0] neg_lo:[0,1] neg_hi:[0,1]
	v_pk_add_f32 v[48:49], v[48:49], v[14:15] op_sel_hi:[1,0] neg_lo:[0,1] neg_hi:[0,1]
	v_pk_add_f32 v[50:51], v[50:51], v[14:15] op_sel_hi:[1,0] neg_lo:[0,1] neg_hi:[0,1]
	v_pk_add_f32 v[52:53], v[52:53], v[14:15] op_sel_hi:[1,0] neg_lo:[0,1] neg_hi:[0,1]
	v_pk_add_f32 v[54:55], v[54:55], v[14:15] op_sel_hi:[1,0] neg_lo:[0,1] neg_hi:[0,1]
	v_pk_add_f32 v[56:57], v[56:57], v[14:15] op_sel_hi:[1,0] neg_lo:[0,1] neg_hi:[0,1]
	v_pk_add_f32 v[58:59], v[58:59], v[14:15] op_sel_hi:[1,0] neg_lo:[0,1] neg_hi:[0,1]
	v_pk_add_f32 v[60:61], v[60:61], v[14:15] op_sel_hi:[1,0] neg_lo:[0,1] neg_hi:[0,1]
	v_pk_add_f32 v[62:63], v[62:63], v[14:15] op_sel_hi:[1,0] neg_lo:[0,1] neg_hi:[0,1]
	v_pk_mul_f32 v[46:47], v[46:47], v[204:205] op_sel_hi:[1,0]
	v_pk_mul_f32 v[44:45], v[44:45], v[204:205] op_sel_hi:[1,0]
	v_pk_mul_f32 v[42:43], v[42:43], v[204:205] op_sel_hi:[1,0]
	v_pk_mul_f32 v[40:41], v[40:41], v[204:205] op_sel_hi:[1,0]
	v_pk_mul_f32 v[38:39], v[38:39], v[204:205] op_sel_hi:[1,0]
	v_pk_mul_f32 v[36:37], v[36:37], v[204:205] op_sel_hi:[1,0]
	v_pk_mul_f32 v[34:35], v[34:35], v[204:205] op_sel_hi:[1,0]
	v_pk_mul_f32 v[32:33], v[32:33], v[204:205] op_sel_hi:[1,0]
	v_pk_mul_f32 v[30:31], v[30:31], v[204:205] op_sel_hi:[1,0]
	v_pk_mul_f32 v[28:29], v[28:29], v[204:205] op_sel_hi:[1,0]
	v_pk_mul_f32 v[26:27], v[26:27], v[204:205] op_sel_hi:[1,0]
	v_pk_mul_f32 v[24:25], v[24:25], v[204:205] op_sel_hi:[1,0]
	v_pk_mul_f32 v[22:23], v[22:23], v[204:205] op_sel_hi:[1,0]
	v_pk_mul_f32 v[20:21], v[20:21], v[204:205] op_sel_hi:[1,0]
	v_pk_mul_f32 v[18:19], v[18:19], v[204:205] op_sel_hi:[1,0]
	v_pk_mul_f32 v[16:17], v[16:17], v[204:205] op_sel_hi:[1,0]
	.p2align	6

; template <bool ROWRMS>
; __device__ __forceinline__ void gemm_mainloop(const u16* __restrict__ A, int lda, const u16* __restrict__ Bt, int ldb,
;                                               int K, f32x16 (&acc)[2][2], char* smem, float* rs) {
;   const int tid = tid_opaque(), lane = tid & 63, w = tid >> 6, wm = w >> 1, wn = w & 1;
;   u16* As = (u16*)smem;
;   u16* Bs = As + 128 * 72;
;   const int r0 = tid >> 3, kc = (tid & 7) * 8;
;   const u16* ga = A + (long)r0 * lda + kc;
;   const u16* gb = Bt + (long)r0 * ldb + kc;
;   const long a32 = 32L * lda, b32 = 32L * ldb;
;   float ss[4] = {0.f, 0.f, 0.f, 0.f};
; #pragma unroll
;   for (int i = 0; i < 2; ++i)
; #pragma unroll
;     for (int j = 0; j < 2; ++j)
; #pragma unroll
;       for (int r = 0; r < 16; ++r) acc[i][j][r] = 0.f;
;   const int nk = K >> 6;
;   const int wofs = r0 * 72 + kc;
;   const int aofs = (wm * 64 + (lane & 31)) * 72 + (lane >> 5) * 8;
;   const int bofs = (wn * 64 + (lane & 31)) * 72 + (lane >> 5) * 8;
;   auto gl = [&](GRegs& R, int kt) {
;     const int ko = kt * 64;
; #pragma unroll
;     for (int i = 0; i < 4; ++i) {
;       R.a[i] = *(const u32x4*)(ga + i * a32 + ko);
;       R.b[i] = *(const u32x4*)(gb + i * b32 + ko);
;     }
;   };
; __device__ __forceinline__ void phaseD(const P& p, int l, char* smem, unsigned* ctr) {
;     ...
;   run_xcd_queues(ctr, 272, 4, smem, [&](int xq, int n) {
;       const int mt = 34 * xq + (n >> 3), nt = n & 7;
;       f32x16 acc[2][2];
;       gemm_mainloop<false>(p.xn + (long)mt * 128 * 1024, 1024, p.wt_out + ((long)l * 1024 + nt * 128) * 1024, 1024, 1024, acc, smem, nullptr);
.LBB0_2262:
	s_or_b64 exec, exec, s[10:11]
	s_waitcnt lgkmcnt(0)
	s_barrier
	ds_read2_b32 v[0:1], v145 offset0:240 offset1:243
	s_mov_b64 s[10:11], -1
	s_waitcnt lgkmcnt(0)
	v_cmp_lt_i32_e32 vcc, s20, v0
	v_readfirstlane_b32 s12, v0
	v_readfirstlane_b32 s14, v1
	s_cbranch_vccnz .LBB0_2271
	s_barrier
	s_and_saveexec_b64 s[10:11], s[0:1]
	s_add_i32 s13, s12, 1
	v_mov_b32_e32 v0, s13
	ds_write_b32 v65, v0 offset:57280
	s_or_b64 exec, exec, s[10:11]
	s_mul_i32 s10, s14, 34
	s_ashr_i32 s11, s12, 3
	s_add_i32 s10, s10, s11
	s_ashr_i32 s11, s10, 31
	s_and_b32 s15, s12, 7
	s_lshl_b64 s[12:13], s[10:11], 18
	s_add_u32 s12, s60, s12
	v_mov_b32_e32 v20, v198
	s_addc_u32 s13, s61, s13
	s_lshl_b32 s11, s15, 18
	s_add_u32 s30, s16, s11
	v_ashrrev_i32_e32 v0, 3, v20
	v_lshlrev_b32_e32 v1, 3, v20
	v_and_b32_e32 v21, 56, v1
	v_ashrrev_i32_e32 v1, 31, v0
	s_addc_u32 s31, s17, 0
	v_lshlrev_b64 v[2:3], 11, v[0:1]
	v_lshl_add_u64 v[4:5], s[30:31], 0, v[2:3]
	v_lshlrev_b32_e32 v64, 1, v21
	v_lshl_add_u64 v[4:5], v[4:5], 0, v[64:65]
	v_lshl_add_u64 v[134:135], s[12:13], 0, v[2:3]
	v_add_co_u32_e32 v8, vcc, s21, v4
	v_lshl_add_u64 v[6:7], v[134:135], 0, v[64:65]
	s_nop 0
	v_addc_co_u32_e32 v9, vcc, 0, v5, vcc
	v_add_co_u32_e32 v10, vcc, s21, v6
	v_mul_lo_u32 v0, v0, s25
	s_nop 0
	v_addc_co_u32_e32 v11, vcc, 0, v7, vcc
	v_add_co_u32_e32 v12, vcc, s22, v4
	v_and_b32_e32 v1, 0x5f, v20
	s_nop 0
	v_addc_co_u32_e32 v13, vcc, 0, v5, vcc
	v_add_co_u32_e32 v14, vcc, s22, v6
	v_add_lshl_u32 v67, v0, v21, 1
	s_nop 0
	v_addc_co_u32_e32 v15, vcc, 0, v7, vcc
	v_add_co_u32_e32 v16, vcc, s23, v4
	s_nop 1
	v_addc_co_u32_e32 v17, vcc, 0, v5, vcc
	v_add_co_u32_e32 v18, vcc, s23, v6
	s_nop 1
	v_addc_co_u32_e32 v19, vcc, 0, v7, vcc
	global_load_dwordx4 v[116:119], v[8:9], off offset:128
	global_load_dwordx4 v[128:131], v[8:9], off
	global_load_dwordx4 v[120:123], v[10:11], off offset:128
	global_load_dwordx4 v[124:127], v[10:11], off
	global_load_dwordx4 v[108:111], v[12:13], off offset:128
	global_load_dwordx4 v[112:115], v[12:13], off
	global_load_dwordx4 v[100:103], v[14:15], off offset:128
	global_load_dwordx4 v[104:107], v[14:15], off
	global_load_dwordx4 v[92:95], v[16:17], off offset:128
	global_load_dwordx4 v[96:99], v[16:17], off
	global_load_dwordx4 v[84:87], v[18:19], off offset:128
	global_load_dwordx4 v[88:91], v[18:19], off
	global_load_dwordx4 v[72:75], v[4:5], off offset:128
	global_load_dwordx4 v[76:79], v[4:5], off
	global_load_dwordx4 v[68:71], v[6:7], off offset:128
	global_load_dwordx4 v[80:83], v[6:7], off
	v_lshrrev_b32_e32 v4, 1, v20
	v_and_b32_e32 v5, 31, v20
	v_and_or_b32 v5, v4, s24, v5
	v_and_b32_e32 v0, 16, v4
	v_mad_u64_u32 v[136:137], s[12:13], v5, s26, v[0:1]
	v_mad_u32_u24 v137, v1, s26, v0
	v_and_b32_e32 v0, 7, v20
	s_add_u32 s12, s52, s11
	v_lshlrev_b32_e32 v64, 4, v0
	s_addc_u32 s13, s53, 0
	v_mov_b32_e32 v0, 0
	v_lshl_add_u64 v[138:139], s[12:13], 0, v[2:3]
	s_mov_b32 s11, -2
	v_mov_b32_e32 v1, v0
	v_mov_b32_e32 v2, v0
	v_mov_b32_e32 v3, v0
	v_mov_b32_e32 v4, v0
	v_mov_b32_e32 v5, v0
	v_mov_b32_e32 v6, v0
	v_mov_b32_e32 v7, v0
	v_mov_b32_e32 v8, v0
	v_mov_b32_e32 v9, v0
	v_mov_b32_e32 v10, v0
	v_mov_b32_e32 v11, v0
	v_mov_b32_e32 v12, v0
	v_mov_b32_e32 v13, v0
	v_mov_b32_e32 v14, v0
	v_mov_b32_e32 v15, v0
	v_mov_b32_e32 v16, v0
	v_mov_b32_e32 v17, v0
	v_mov_b32_e32 v18, v0
	v_mov_b32_e32 v19, v0
	v_mov_b32_e32 v20, v0
	v_mov_b32_e32 v21, v0
	v_mov_b32_e32 v22, v0
	v_mov_b32_e32 v23, v0
	v_mov_b32_e32 v24, v0
	v_mov_b32_e32 v25, v0
	v_mov_b32_e32 v26, v0
	v_mov_b32_e32 v27, v0
	v_mov_b32_e32 v28, v0
	v_mov_b32_e32 v29, v0
	v_mov_b32_e32 v30, v0
	v_mov_b32_e32 v31, v0
	v_mov_b32_e32 v32, v0
	v_mov_b32_e32 v33, v0
	v_mov_b32_e32 v34, v0
	v_mov_b32_e32 v35, v0
	v_mov_b32_e32 v36, v0
	v_mov_b32_e32 v37, v0
	v_mov_b32_e32 v38, v0
	v_mov_b32_e32 v39, v0
	v_mov_b32_e32 v40, v0
	v_mov_b32_e32 v41, v0
	v_mov_b32_e32 v42, v0
	v_mov_b32_e32 v43, v0
	v_mov_b32_e32 v44, v0
	v_mov_b32_e32 v45, v0
	v_mov_b32_e32 v46, v0
	v_mov_b32_e32 v47, v0
	v_mov_b32_e32 v48, v0
	v_mov_b32_e32 v49, v0
	v_mov_b32_e32 v50, v0
	v_mov_b32_e32 v51, v0
	v_mov_b32_e32 v52, v0
	v_mov_b32_e32 v53, v0
	v_mov_b32_e32 v54, v0
	v_mov_b32_e32 v55, v0
	v_mov_b32_e32 v56, v0
	v_mov_b32_e32 v57, v0
	v_mov_b32_e32 v58, v0
	v_mov_b32_e32 v59, v0
	v_mov_b32_e32 v60, v0
	v_mov_b32_e32 v61, v0
	v_mov_b32_e32 v62, v0
	v_mov_b32_e32 v63, v0
	s_branch .LBB0_2267
	.p2align	6
